# indexer: the four max/min butterflies after the score loop run in lock-step (5 LDS round trips instead of 20)
# speedup vs baseline: 1.0130x; 1.0023x over previous
; __device__ __forceinline__ void indexer_phase(const bf16_t* PJ, float* rk, unsigned short* SEL, LAS unsigned char* lds) {
;     ...
; #pragma unroll
;             for (int rt = 0; rt < 2; ++rt)
; #pragma unroll
;                 for (int qq = 0; qq < 2; ++qq) {
; #pragma unroll
;                     for (int o = 1; o < 32; o <<= 1) { rmax[rt][qq] = fmaxf(rmax[rt][qq], __shfl_xor(rmax[rt][qq], o)); rmin[rt][qq] = fminf(rmin[rt][qq], __shfl_xor(rmin[rt][qq], o)); }
;                     if (r32 == 0) { pmm[(wid * 8 + 4 * rt + 2 * hi + qq) * 2] = rmax[rt][qq]; pmm[(wid * 8 + 4 * rt + 2 * hi + qq) * 2 + 1] = rmin[rt][qq]; } }
.LBB0_874:
	s_waitcnt lgkmcnt(0)
	v_and_b32_e32 v11, 64, v180
	v_add_u32_e32 v0, 64, v11
	v_xor_b32_e32 v4, 1, v180
	v_cmp_lt_i32_e32 vcc, v4, v0
	s_nop 1
	v_cndmask_b32_e32 v4, v180, v4, vcc
	v_lshlrev_b32_e32 v20, 2, v4
	v_xor_b32_e32 v4, 2, v180
	v_cmp_lt_i32_e32 vcc, v4, v0
	s_nop 1
	v_cndmask_b32_e32 v4, v180, v4, vcc
	v_lshlrev_b32_e32 v21, 2, v4
	v_xor_b32_e32 v4, 4, v180
	v_cmp_lt_i32_e32 vcc, v4, v0
	s_nop 1
	v_cndmask_b32_e32 v4, v180, v4, vcc
	v_lshlrev_b32_e32 v22, 2, v4
	v_xor_b32_e32 v4, 8, v180
	v_cmp_lt_i32_e32 vcc, v4, v0
	s_nop 1
	v_cndmask_b32_e32 v4, v180, v4, vcc
	v_lshlrev_b32_e32 v23, 2, v4
	v_xor_b32_e32 v4, 16, v180
	v_cmp_lt_i32_e32 vcc, v4, v0
	s_nop 1
	v_cndmask_b32_e32 v4, v180, v4, vcc
	v_lshlrev_b32_e32 v24, 2, v4
	ds_bpermute_b32 v12, v20, v189
	ds_bpermute_b32 v13, v20, v188
	ds_bpermute_b32 v14, v20, v187
	ds_bpermute_b32 v15, v20, v186
	ds_bpermute_b32 v16, v20, v185
	ds_bpermute_b32 v17, v20, v184
	ds_bpermute_b32 v18, v20, v183
	ds_bpermute_b32 v19, v20, v123
	s_waitcnt lgkmcnt(0)
	v_max_f32_e32 v189, v189, v12
	v_min_f32_e32 v188, v188, v13
	v_max_f32_e32 v187, v187, v14
	v_min_f32_e32 v186, v186, v15
	v_max_f32_e32 v185, v185, v16
	v_min_f32_e32 v184, v184, v17
	v_max_f32_e32 v183, v183, v18
	v_min_f32_e32 v123, v123, v19
	ds_bpermute_b32 v12, v21, v189
	ds_bpermute_b32 v13, v21, v188
	ds_bpermute_b32 v14, v21, v187
	ds_bpermute_b32 v15, v21, v186
	ds_bpermute_b32 v16, v21, v185
	ds_bpermute_b32 v17, v21, v184
	ds_bpermute_b32 v18, v21, v183
	ds_bpermute_b32 v19, v21, v123
	s_waitcnt lgkmcnt(0)
	v_max_f32_e32 v189, v189, v12
	v_min_f32_e32 v188, v188, v13
	v_max_f32_e32 v187, v187, v14
	v_min_f32_e32 v186, v186, v15
	v_max_f32_e32 v185, v185, v16
	v_min_f32_e32 v184, v184, v17
	v_max_f32_e32 v183, v183, v18
	v_min_f32_e32 v123, v123, v19
	ds_bpermute_b32 v12, v22, v189
	ds_bpermute_b32 v13, v22, v188
	ds_bpermute_b32 v14, v22, v187
	ds_bpermute_b32 v15, v22, v186
	ds_bpermute_b32 v16, v22, v185
	ds_bpermute_b32 v17, v22, v184
	ds_bpermute_b32 v18, v22, v183
	ds_bpermute_b32 v19, v22, v123
	s_waitcnt lgkmcnt(0)
	v_max_f32_e32 v189, v189, v12
	v_min_f32_e32 v188, v188, v13
	v_max_f32_e32 v187, v187, v14
	v_min_f32_e32 v186, v186, v15
	v_max_f32_e32 v185, v185, v16
	v_min_f32_e32 v184, v184, v17
	v_max_f32_e32 v183, v183, v18
	v_min_f32_e32 v123, v123, v19
	ds_bpermute_b32 v12, v23, v189
	ds_bpermute_b32 v13, v23, v188
	ds_bpermute_b32 v14, v23, v187
	ds_bpermute_b32 v15, v23, v186
	ds_bpermute_b32 v16, v23, v185
	ds_bpermute_b32 v17, v23, v184
	ds_bpermute_b32 v18, v23, v183
	ds_bpermute_b32 v19, v23, v123
	s_waitcnt lgkmcnt(0)
	v_max_f32_e32 v189, v189, v12
	v_min_f32_e32 v188, v188, v13
	v_max_f32_e32 v187, v187, v14
	v_min_f32_e32 v186, v186, v15
	v_max_f32_e32 v185, v185, v16
	v_min_f32_e32 v184, v184, v17
	v_max_f32_e32 v183, v183, v18
	v_min_f32_e32 v123, v123, v19
	ds_bpermute_b32 v12, v24, v189
	ds_bpermute_b32 v13, v24, v188
	ds_bpermute_b32 v14, v24, v187
	ds_bpermute_b32 v15, v24, v186
	ds_bpermute_b32 v16, v24, v185
	ds_bpermute_b32 v17, v24, v184
	ds_bpermute_b32 v18, v24, v183
	ds_bpermute_b32 v19, v24, v123
	s_waitcnt lgkmcnt(0)
	v_max_f32_e32 v2, v189, v12
	v_min_f32_e32 v3, v188, v13
	v_max_f32_e32 v4, v187, v14
	v_min_f32_e32 v5, v186, v15
	v_max_f32_e32 v6, v185, v16
	v_min_f32_e32 v7, v184, v17
	v_max_f32_e32 v8, v183, v18
	v_min_f32_e32 v9, v123, v19
	s_and_saveexec_b64 s[24:25], s[8:9]
	s_cbranch_execz .LBB0_882
	v_add_u32_e32 v1, 0x26000, v160
	ds_write_b64 v1, v[2:3]
	ds_write_b64 v1, v[4:5] offset:8
	ds_write_b64 v1, v[6:7] offset:32
	ds_write_b64 v1, v[8:9] offset:40
